# stack42 + P3 tail: gate-weight staging loop turned into 8(+1) loads in flight with counted waits (was 8-9 dependent round trips)
# baseline (speedup 1.0000x reference)
.LBB0_403:
	global_load_dwordx4 v[64:67], v[0:1], off
	v_lshl_add_u64 v[0:1], v[0:1], 0, s[6:7]
	global_load_dwordx4 v[68:71], v[0:1], off
	v_lshl_add_u64 v[0:1], v[0:1], 0, s[6:7]
	global_load_dwordx4 v[72:75], v[0:1], off
	v_lshl_add_u64 v[0:1], v[0:1], 0, s[6:7]
	global_load_dwordx4 v[76:79], v[0:1], off
	v_lshl_add_u64 v[0:1], v[0:1], 0, s[6:7]
	global_load_dwordx4 v[80:83], v[0:1], off
	v_lshl_add_u64 v[0:1], v[0:1], 0, s[6:7]
	global_load_dwordx4 v[84:87], v[0:1], off
	v_lshl_add_u64 v[0:1], v[0:1], 0, s[6:7]
	global_load_dwordx4 v[88:91], v[0:1], off
	v_lshl_add_u64 v[0:1], v[0:1], 0, s[6:7]
	global_load_dwordx4 v[92:95], v[0:1], off
	v_lshl_add_u64 v[0:1], v[0:1], 0, s[6:7]
	v_add_u32_e32 v3, 0x1000, v3
	v_cmp_ge_i32_e32 vcc, s14, v3
	s_and_saveexec_b64 s[4:5], vcc
	global_load_dwordx4 v[96:99], v[0:1], off
	s_or_b64 exec, exec, s[4:5]
	s_waitcnt vmcnt(7)
	ds_write_b128 v4, v[64:67]
	s_waitcnt vmcnt(6)
	ds_write_b128 v4, v[68:71] offset:8192
	s_waitcnt vmcnt(5)
	ds_write_b128 v4, v[72:75] offset:16384
	s_waitcnt vmcnt(4)
	ds_write_b128 v4, v[76:79] offset:24576
	s_waitcnt vmcnt(3)
	ds_write_b128 v4, v[80:83] offset:32768
	s_waitcnt vmcnt(2)
	ds_write_b128 v4, v[84:87] offset:40960
	s_waitcnt vmcnt(1)
	ds_write_b128 v4, v[88:91] offset:49152
	s_waitcnt vmcnt(0)
	ds_write_b128 v4, v[92:95] offset:57344
	s_and_saveexec_b64 s[4:5], vcc
	v_add_u32_e32 v100, 0x10000, v4
	s_waitcnt vmcnt(0)
	ds_write_b128 v100, v[96:99]
	s_or_b64 exec, exec, s[4:5]
	v_mov_b32_e32 v0, s11
